# hg_local: the 32 V^T element loads of the KT/VT build loop are issued together before the loop and written to LDS after it (was one exposed global load per iteration)
# speedup vs baseline: 1.0061x; 1.0022x over previous
; __device__ __forceinline__ float sigmoidf_(float x) { return 1.0f / (1.0f + __expf(-x)); }
; __device__ __forceinline__ void hg_bcum(const Params& p, int l, const u16* Uhg, int t0, int h, float* bc, float* lbs,
;                                         float* tots) {
;     ...
;   __syncthreads();
; #pragma unroll
;   for (int k = 0; k < 4; ++k) {
;     const int s = (tid >> 4) + 16 * k, d0 = (tid & 15) * 8;
;     float z[8];
;     unpack8(*(const uint4*)(Uhg + (size_t)(t0 + s) * 2048 + 512 + h * 128 + d0), z);
;     float lf[8];
; #pragma unroll
;     for (int j = 0; j < 8; ++j) {
;       const float lbv = lbs[d0 + j];
;       const float f = lbv + (1.0f - lbv) * sigmoidf_(z[j]);
;       lf[j] = __logf(fmaxf(f, 1e-30f));
;     }
;     *(float4*)(bc + s * BCS + d0) = make_float4(lf[0], lf[1], lf[2], lf[3]);
;     *(float4*)(bc + s * BCS + d0 + 4) = make_float4(lf[4], lf[5], lf[6], lf[7]);
.LBB0_381:
	s_or_b64 exec, exec, s[0:1]
	s_lshl_b32 s0, s48, 4
	s_lshl_b32 s1, s48, 6
	s_and_b32 s0, s0, 0xffffe000
	s_and_b32 s1, s1, 0x1fc0
	s_or_b32 s0, s0, s1
	v_lshrrev_b32_e32 v35, 4, v2
	v_or_b32_e32 v14, s0, v35
	v_lshlrev_b32_e32 v2, 3, v18
	v_ashrrev_i32_e32 v15, 31, v14
	v_readlane_b32 s22, v252, 46
	v_and_b32_e32 v4, 0x78, v2
	v_lshlrev_b64 v[2:3], 12, v[14:15]
	v_readlane_b32 s23, v252, 47
	s_lshl_b32 s58, s10, 8
	v_lshlrev_b32_e32 v16, 1, v4
	v_lshl_add_u64 v[2:3], s[22:23], 0, v[2:3]
	v_lshl_add_u64 v[2:3], v[2:3], 0, s[58:59]
	v_mov_b32_e32 v17, v1
	v_lshl_add_u64 v[2:3], v[2:3], 0, v[16:17]
	s_waitcnt lgkmcnt(0)
	s_barrier
	v_lshl_add_u32 v37, v4, 2, s69
	global_load_dwordx4 v[2:5], v[2:3], off offset:1024
	v_and_b32_e32 v80, 0x7f, v18
	s_waitcnt vmcnt(0)
	v_lshlrev_b32_e32 v10, 16, v2
	v_mul_f32_e32 v10, 0xbfb8aa3b, v10
	v_exp_f32_e32 v10, v10
	v_and_b32_e32 v11, 0xffff0000, v2
	v_lshlrev_b32_e32 v12, 16, v3
	v_and_b32_e32 v13, 0xffff0000, v3
	v_add_f32_e32 v10, 1.0, v10
	v_div_scale_f32 v20, s[0:1], v10, v10, 1.0
	v_rcp_f32_e32 v21, v20
	v_lshlrev_b32_e32 v15, 16, v4
	v_and_b32_e32 v19, 0xffff0000, v4
	v_lshlrev_b32_e32 v39, 16, v5
	v_fma_f32 v22, -v20, v21, 1.0
	v_fmac_f32_e32 v21, v22, v21
	v_div_scale_f32 v22, vcc, 1.0, v10, 1.0
	v_mul_f32_e32 v23, v22, v21
	v_and_b32_e32 v41, 0xffff0000, v5
	ds_read_b128 v[6:9], v37 offset:33792
	ds_read_b128 v[2:5], v37 offset:33808
	v_fma_f32 v24, -v20, v23, v22
	v_fmac_f32_e32 v23, v24, v21
	v_fma_f32 v20, -v20, v23, v22
	v_div_fmas_f32 v20, v20, v21, v23
	s_waitcnt lgkmcnt(1)
	v_sub_f32_e32 v33, 1.0, v6
	v_div_fixup_f32 v10, v20, v10, 1.0
	v_fma_f32 v10, v33, v10, v6
	v_max_f32_e32 v10, 0xda24260, v10
	v_cmp_gt_f32_e32 vcc, s56, v10
	v_mul_f32_e32 v11, 0xbfb8aa3b, v11
	v_exp_f32_e32 v11, v11
	v_cndmask_b32_e64 v20, 0, 32, vcc
	v_ldexp_f32 v10, v10, v20
	v_log_f32_e32 v10, v10
	v_add_f32_e32 v11, 1.0, v11
	v_sub_f32_e32 v25, 1.0, v7
	v_mul_f32_e32 v12, 0xbfb8aa3b, v12
	v_mul_f32_e32 v20, 0x3f317217, v10
	v_fma_f32 v20, v10, s57, -v20
	v_fmac_f32_e32 v20, 0x3377d1cf, v10
	v_fmac_f32_e32 v20, 0x3f317217, v10
	v_cmp_lt_f32_e64 s[0:1], |v10|, s8
	v_exp_f32_e32 v12, v12
	v_mul_f32_e32 v13, 0xbfb8aa3b, v13
	v_cndmask_b32_e64 v10, v10, v20, s[0:1]
	v_cndmask_b32_e32 v20, 0, v201, vcc
	v_sub_f32_e32 v10, v10, v20
	v_div_scale_f32 v20, s[0:1], v11, v11, 1.0
	v_rcp_f32_e32 v21, v20
	v_add_f32_e32 v12, 1.0, v12
	v_exp_f32_e32 v13, v13
	v_mul_f32_e32 v15, 0xbfb8aa3b, v15
	v_fma_f32 v22, -v20, v21, 1.0
	v_fmac_f32_e32 v21, v22, v21
	v_div_scale_f32 v22, vcc, 1.0, v11, 1.0
	v_mul_f32_e32 v23, v22, v21
	v_fma_f32 v24, -v20, v23, v22
	v_fmac_f32_e32 v23, v24, v21
	v_fma_f32 v20, -v20, v23, v22
	v_div_fmas_f32 v20, v20, v21, v23
	v_div_fixup_f32 v11, v20, v11, 1.0
	v_fma_f32 v11, v11, v25, v7
	v_max_f32_e32 v11, 0xda24260, v11
	v_cmp_gt_f32_e32 vcc, s56, v11
	v_sub_f32_e32 v24, 1.0, v8
	v_add_f32_e32 v13, 1.0, v13
	v_cndmask_b32_e64 v20, 0, 32, vcc
	v_ldexp_f32 v11, v11, v20
	v_log_f32_e32 v11, v11
	v_exp_f32_e32 v15, v15
	v_mul_f32_e32 v20, 0x3f317217, v11
	v_fma_f32 v20, v11, s57, -v20
	v_fmac_f32_e32 v20, 0x3377d1cf, v11
	v_fmac_f32_e32 v20, 0x3f317217, v11
	v_cmp_lt_f32_e64 s[0:1], |v11|, s8
	v_add_f32_e32 v15, 1.0, v15
	s_nop 0
	v_cndmask_b32_e64 v11, v11, v20, s[0:1]
	v_cndmask_b32_e32 v20, 0, v201, vcc
	v_sub_f32_e32 v11, v11, v20
	v_div_scale_f32 v20, s[0:1], v12, v12, 1.0
	v_rcp_f32_e32 v21, v20
	s_nop 0
	v_fma_f32 v22, -v20, v21, 1.0
	v_fmac_f32_e32 v21, v22, v21
	v_div_scale_f32 v22, vcc, 1.0, v12, 1.0
	v_mul_f32_e32 v23, v22, v21
	v_fma_f32 v43, -v20, v23, v22
	v_fmac_f32_e32 v23, v43, v21
	v_fma_f32 v20, -v20, v23, v22
	v_div_fmas_f32 v20, v20, v21, v23
	v_div_fixup_f32 v12, v20, v12, 1.0
	v_fma_f32 v12, v12, v24, v8
	v_max_f32_e32 v12, 0xda24260, v12
	v_cmp_gt_f32_e32 vcc, s56, v12
	v_sub_f32_e32 v23, 1.0, v9
	s_nop 0
	v_cndmask_b32_e64 v20, 0, 32, vcc
	v_ldexp_f32 v12, v12, v20
	v_log_f32_e32 v12, v12
	s_nop 0
	v_mul_f32_e32 v20, 0x3f317217, v12
	v_fma_f32 v20, v12, s57, -v20
	v_fmac_f32_e32 v20, 0x3377d1cf, v12
	v_fmac_f32_e32 v20, 0x3f317217, v12
	v_cmp_lt_f32_e64 s[0:1], |v12|, s8
	s_nop 1
	v_cndmask_b32_e64 v12, v12, v20, s[0:1]
	v_cndmask_b32_e32 v20, 0, v201, vcc
	v_sub_f32_e32 v12, v12, v20
	v_div_scale_f32 v20, s[0:1], v13, v13, 1.0
	v_rcp_f32_e32 v21, v20
	s_nop 0
	v_fma_f32 v22, -v20, v21, 1.0
	v_fmac_f32_e32 v21, v22, v21
	v_div_scale_f32 v22, vcc, 1.0, v13, 1.0
	v_mul_f32_e32 v43, v22, v21
	v_fma_f32 v45, -v20, v43, v22
	v_fmac_f32_e32 v43, v45, v21
	v_fma_f32 v20, -v20, v43, v22
	v_div_fmas_f32 v20, v20, v21, v43
	v_div_fixup_f32 v13, v20, v13, 1.0
	v_fma_f32 v13, v13, v23, v9
	v_max_f32_e32 v13, 0xda24260, v13
	v_cmp_gt_f32_e32 vcc, s56, v13
	s_waitcnt lgkmcnt(0)
; __device__ __forceinline__ float sigmoidf_(float x) { return 1.0f / (1.0f + __expf(-x)); }
; __device__ __forceinline__ void hg_bcum(const Params& p, int l, const u16* Uhg, int t0, int h, float* bc, float* lbs,
;                                         float* tots) {
;     ...
;   for (int k = 0; k < 4; ++k) {
;     const int s = (tid >> 4) + 16 * k, d0 = (tid & 15) * 8;
;     float z[8];
;     unpack8(*(const uint4*)(Uhg + (size_t)(t0 + s) * 2048 + 512 + h * 128 + d0), z);
;     float lf[8];
; #pragma unroll
;     for (int j = 0; j < 8; ++j) {
;       const float lbv = lbs[d0 + j];
;       const float f = lbv + (1.0f - lbv) * sigmoidf_(z[j]);
;       lf[j] = __logf(fmaxf(f, 1e-30f));
;     }
;     *(float4*)(bc + s * BCS + d0) = make_float4(lf[0], lf[1], lf[2], lf[3]);
;     *(float4*)(bc + s * BCS + d0 + 4) = make_float4(lf[4], lf[5], lf[6], lf[7]);
	v_sub_f32_e32 v22, 1.0, v2
	v_cndmask_b32_e64 v20, 0, 32, vcc
	v_ldexp_f32 v13, v13, v20
	v_log_f32_e32 v13, v13
	s_nop 0
	v_mul_f32_e32 v20, 0x3f317217, v13
	v_fma_f32 v20, v13, s57, -v20
	v_fmac_f32_e32 v20, 0x3377d1cf, v13
	v_fmac_f32_e32 v20, 0x3f317217, v13
	v_cmp_lt_f32_e64 s[0:1], |v13|, s8
	s_nop 1
	v_cndmask_b32_e64 v13, v13, v20, s[0:1]
	v_cndmask_b32_e32 v20, 0, v201, vcc
	v_sub_f32_e32 v13, v13, v20
	v_div_scale_f32 v20, s[0:1], v15, v15, 1.0
	v_rcp_f32_e32 v21, v20
	s_nop 0
	v_fma_f32 v43, -v20, v21, 1.0
	v_fmac_f32_e32 v21, v43, v21
	v_div_scale_f32 v43, vcc, 1.0, v15, 1.0
	v_mul_f32_e32 v45, v43, v21
	v_fma_f32 v62, -v20, v45, v43
	v_fmac_f32_e32 v45, v62, v21
	v_fma_f32 v20, -v20, v45, v43
	v_div_fmas_f32 v20, v20, v21, v45
	v_div_fixup_f32 v15, v20, v15, 1.0
	v_fma_f32 v15, v15, v22, v2
	v_max_f32_e32 v15, 0xda24260, v15
	v_cmp_gt_f32_e32 vcc, s56, v15
	v_sub_f32_e32 v21, 1.0, v3
	s_nop 0
	v_cndmask_b32_e64 v20, 0, 32, vcc
	v_ldexp_f32 v15, v15, v20
	v_log_f32_e32 v15, v15
	s_nop 0
	v_mul_f32_e32 v20, 0x3f317217, v15
	v_fma_f32 v20, v15, s57, -v20
	v_fmac_f32_e32 v20, 0x3377d1cf, v15
	v_fmac_f32_e32 v20, 0x3f317217, v15
	v_cmp_lt_f32_e64 s[0:1], |v15|, s8
	s_nop 1
	v_cndmask_b32_e64 v15, v15, v20, s[0:1]
	v_cndmask_b32_e32 v20, 0, v201, vcc
	v_sub_f32_e32 v62, v15, v20
	v_mul_f32_e32 v15, 0xbfb8aa3b, v19
	v_exp_f32_e32 v15, v15
	s_nop 0
	v_add_f32_e32 v15, 1.0, v15
	v_div_scale_f32 v19, s[0:1], v15, v15, 1.0
	v_rcp_f32_e32 v20, v19
	s_nop 0
	v_fma_f32 v43, -v19, v20, 1.0
	v_fmac_f32_e32 v20, v43, v20
	v_div_scale_f32 v43, vcc, 1.0, v15, 1.0
	v_mul_f32_e32 v45, v43, v20
	v_fma_f32 v63, -v19, v45, v43
	v_fmac_f32_e32 v45, v63, v20
	v_fma_f32 v19, -v19, v45, v43
	v_div_fmas_f32 v19, v19, v20, v45
	v_div_fixup_f32 v15, v19, v15, 1.0
	v_fma_f32 v15, v15, v21, v3
	v_max_f32_e32 v15, 0xda24260, v15
	v_cmp_gt_f32_e32 vcc, s56, v15
	v_sub_f32_e32 v20, 1.0, v4
	s_nop 0
	v_cndmask_b32_e64 v19, 0, 32, vcc
	v_ldexp_f32 v15, v15, v19
	v_log_f32_e32 v15, v15
	s_nop 0
	v_mul_f32_e32 v19, 0x3f317217, v15
	v_fma_f32 v19, v15, s57, -v19
	v_fmac_f32_e32 v19, 0x3377d1cf, v15
	v_fmac_f32_e32 v19, 0x3f317217, v15
	v_cmp_lt_f32_e64 s[0:1], |v15|, s8
	s_nop 1
	v_cndmask_b32_e64 v15, v15, v19, s[0:1]
	v_cndmask_b32_e32 v19, 0, v201, vcc
	v_sub_f32_e32 v63, v15, v19
	v_mul_f32_e32 v15, 0xbfb8aa3b, v39
	v_exp_f32_e32 v15, v15
	s_nop 0
	v_add_f32_e32 v15, 1.0, v15
	v_div_scale_f32 v19, s[0:1], v15, v15, 1.0
	v_rcp_f32_e32 v39, v19
	s_nop 0
	v_fma_f32 v43, -v19, v39, 1.0
	v_fmac_f32_e32 v39, v43, v39
	v_div_scale_f32 v43, vcc, 1.0, v15, 1.0
	v_mul_f32_e32 v45, v43, v39
	v_fma_f32 v64, -v19, v45, v43
	v_fmac_f32_e32 v45, v64, v39
	v_fma_f32 v19, -v19, v45, v43
	v_div_fmas_f32 v19, v19, v39, v45
	v_div_fixup_f32 v15, v19, v15, 1.0
	v_fma_f32 v15, v15, v20, v4
	v_max_f32_e32 v15, 0xda24260, v15
	v_cmp_gt_f32_e32 vcc, s56, v15
	s_nop 1
	v_cndmask_b32_e64 v19, 0, 32, vcc
	v_ldexp_f32 v15, v15, v19
	v_log_f32_e32 v15, v15
	s_nop 0
	v_mul_f32_e32 v19, 0x3f317217, v15
	v_fma_f32 v19, v15, s57, -v19
	v_fmac_f32_e32 v19, 0x3377d1cf, v15
	v_fmac_f32_e32 v19, 0x3f317217, v15
	v_cmp_lt_f32_e64 s[0:1], |v15|, s8
	s_nop 1
	v_cndmask_b32_e64 v15, v15, v19, s[0:1]
	v_cndmask_b32_e32 v19, 0, v201, vcc
	v_sub_f32_e32 v64, v15, v19
	v_mul_f32_e32 v15, 0xbfb8aa3b, v41
	v_exp_f32_e32 v15, v15
	v_sub_f32_e32 v19, 1.0, v5
	v_add_f32_e32 v15, 1.0, v15
	v_div_scale_f32 v39, s[0:1], v15, v15, 1.0
	v_rcp_f32_e32 v41, v39
	s_nop 0
	v_fma_f32 v43, -v39, v41, 1.0
	v_fmac_f32_e32 v41, v43, v41
	v_div_scale_f32 v43, vcc, 1.0, v15, 1.0
	v_mul_f32_e32 v45, v43, v41
	v_fma_f32 v65, -v39, v45, v43
	v_fmac_f32_e32 v45, v65, v41
	v_fma_f32 v39, -v39, v45, v43
	v_div_fmas_f32 v39, v39, v41, v45
	v_div_fixup_f32 v15, v39, v15, 1.0
	v_fma_f32 v15, v15, v19, v5
	v_max_f32_e32 v15, 0xda24260, v15
	v_cmp_gt_f32_e32 vcc, s56, v15
	s_nop 1
	v_cndmask_b32_e64 v39, 0, 32, vcc
	v_ldexp_f32 v15, v15, v39
	v_log_f32_e32 v15, v15
	s_nop 0
	v_mul_f32_e32 v39, 0x3f317217, v15
	v_fma_f32 v39, v15, s57, -v39
	v_fmac_f32_e32 v39, 0x3377d1cf, v15
	v_fmac_f32_e32 v39, 0x3f317217, v15
	v_cmp_lt_f32_e64 s[0:1], |v15|, s8
	s_nop 1
	v_cndmask_b32_e64 v15, v15, v39, s[0:1]
	v_cndmask_b32_e32 v39, 0, v201, vcc
	v_sub_f32_e32 v65, v15, v39
	v_mad_u32_u24 v15, v35, s2, v37
	ds_write_b128 v15, v[10:13]
	ds_write_b128 v15, v[62:65] offset:16
	v_or_b32_e32 v10, 16, v14
	v_ashrrev_i32_e32 v11, 31, v10
	v_lshlrev_b64 v[10:11], 12, v[10:11]
	v_lshl_add_u64 v[10:11], s[22:23], 0, v[10:11]
	v_lshl_add_u64 v[10:11], v[10:11], 0, s[58:59]
	v_lshl_add_u64 v[10:11], v[10:11], 0, v[16:17]
	global_load_dwordx4 v[10:13], v[10:11], off offset:1024
	s_waitcnt vmcnt(0)
; __device__ __forceinline__ float sigmoidf_(float x) { return 1.0f / (1.0f + __expf(-x)); }
; __device__ __forceinline__ void hg_bcum(const Params& p, int l, const u16* Uhg, int t0, int h, float* bc, float* lbs,
;                                         float* tots) {
;     ...
;   for (int k = 0; k < 4; ++k) {
;     const int s = (tid >> 4) + 16 * k, d0 = (tid & 15) * 8;
;     float z[8];
;     unpack8(*(const uint4*)(Uhg + (size_t)(t0 + s) * 2048 + 512 + h * 128 + d0), z);
;     float lf[8];
; #pragma unroll
;     for (int j = 0; j < 8; ++j) {
;       const float lbv = lbs[d0 + j];
;       const float f = lbv + (1.0f - lbv) * sigmoidf_(z[j]);
;       lf[j] = __logf(fmaxf(f, 1e-30f));
;     }
;     *(float4*)(bc + s * BCS + d0) = make_float4(lf[0], lf[1], lf[2], lf[3]);
;     *(float4*)(bc + s * BCS + d0 + 4) = make_float4(lf[4], lf[5], lf[6], lf[7]);
	v_lshlrev_b32_e32 v39, 16, v10
	v_and_b32_e32 v41, 0xffff0000, v10
	v_mul_f32_e32 v10, 0xbfb8aa3b, v39
	v_exp_f32_e32 v10, v10
	v_lshlrev_b32_e32 v43, 16, v11
	v_and_b32_e32 v45, 0xffff0000, v11
	v_lshlrev_b32_e32 v62, 16, v12
	v_add_f32_e32 v10, 1.0, v10
	v_div_scale_f32 v11, s[0:1], v10, v10, 1.0
	v_and_b32_e32 v63, 0xffff0000, v12
	v_rcp_f32_e32 v12, v11
	v_lshlrev_b32_e32 v37, 16, v13
	v_and_b32_e32 v35, 0xffff0000, v13
	v_mul_f32_e32 v37, 0xbfb8aa3b, v37
	v_fma_f32 v13, -v11, v12, 1.0
	v_fmac_f32_e32 v12, v13, v12
	v_div_scale_f32 v13, vcc, 1.0, v10, 1.0
	v_mul_f32_e32 v39, v13, v12
	v_fma_f32 v64, -v11, v39, v13
	v_fmac_f32_e32 v39, v64, v12
	v_fma_f32 v11, -v11, v39, v13
	v_div_fmas_f32 v11, v11, v12, v39
	v_div_fixup_f32 v10, v11, v10, 1.0
	v_fma_f32 v10, v33, v10, v6
	v_max_f32_e32 v10, 0xda24260, v10
	v_cmp_gt_f32_e32 vcc, s56, v10
	v_exp_f32_e32 v37, v37
	v_mul_f32_e32 v35, 0xbfb8aa3b, v35
	v_cndmask_b32_e64 v11, 0, 32, vcc
	v_ldexp_f32 v10, v10, v11
	v_log_f32_e32 v10, v10
	v_add_f32_e32 v37, 1.0, v37
	v_exp_f32_e32 v35, v35
	v_mul_f32_e32 v11, 0x3f317217, v10
	v_fma_f32 v11, v10, s57, -v11
	v_fmac_f32_e32 v11, 0x3377d1cf, v10
	v_fmac_f32_e32 v11, 0x3f317217, v10
	v_cmp_lt_f32_e64 s[0:1], |v10|, s8
	v_add_f32_e32 v35, 1.0, v35
	s_nop 0
	v_cndmask_b32_e64 v10, v10, v11, s[0:1]
	v_cndmask_b32_e32 v11, 0, v201, vcc
	v_sub_f32_e32 v10, v10, v11
	v_mul_f32_e32 v11, 0xbfb8aa3b, v41
	v_exp_f32_e32 v11, v11
	s_nop 0
	v_add_f32_e32 v11, 1.0, v11
	v_div_scale_f32 v12, s[0:1], v11, v11, 1.0
	v_rcp_f32_e32 v13, v12
	s_nop 0
	v_fma_f32 v39, -v12, v13, 1.0
	v_fmac_f32_e32 v13, v39, v13
	v_div_scale_f32 v39, vcc, 1.0, v11, 1.0
	v_mul_f32_e32 v41, v39, v13
	v_fma_f32 v64, -v12, v41, v39
	v_fmac_f32_e32 v41, v64, v13
	v_fma_f32 v12, -v12, v41, v39
	v_div_fmas_f32 v12, v12, v13, v41
	v_div_fixup_f32 v11, v12, v11, 1.0
	v_fma_f32 v11, v25, v11, v7
	v_max_f32_e32 v11, 0xda24260, v11
	v_cmp_gt_f32_e32 vcc, s56, v11
	s_nop 1
	v_cndmask_b32_e64 v12, 0, 32, vcc
	v_ldexp_f32 v11, v11, v12
	v_log_f32_e32 v11, v11
	s_nop 0
	v_mul_f32_e32 v12, 0x3f317217, v11
	v_fma_f32 v12, v11, s57, -v12
	v_fmac_f32_e32 v12, 0x3377d1cf, v11
	v_fmac_f32_e32 v12, 0x3f317217, v11
	v_cmp_lt_f32_e64 s[0:1], |v11|, s8
	s_nop 1
	v_cndmask_b32_e64 v11, v11, v12, s[0:1]
	v_cndmask_b32_e32 v12, 0, v201, vcc
	v_sub_f32_e32 v11, v11, v12
	v_mul_f32_e32 v12, 0xbfb8aa3b, v43
	v_exp_f32_e32 v12, v12
	s_nop 0
	v_add_f32_e32 v12, 1.0, v12
	v_div_scale_f32 v13, s[0:1], v12, v12, 1.0
	v_rcp_f32_e32 v39, v13
	s_nop 0
	v_fma_f32 v41, -v13, v39, 1.0
	v_fmac_f32_e32 v39, v41, v39
	v_div_scale_f32 v41, vcc, 1.0, v12, 1.0
	v_mul_f32_e32 v43, v41, v39
	v_fma_f32 v64, -v13, v43, v41
	v_fmac_f32_e32 v43, v64, v39
	v_fma_f32 v13, -v13, v43, v41
	v_div_fmas_f32 v13, v13, v39, v43
	v_div_fixup_f32 v12, v13, v12, 1.0
	v_fma_f32 v12, v24, v12, v8
	v_max_f32_e32 v12, 0xda24260, v12
	v_cmp_gt_f32_e32 vcc, s56, v12
	s_nop 1
	v_cndmask_b32_e64 v13, 0, 32, vcc
	v_ldexp_f32 v12, v12, v13
	v_log_f32_e32 v12, v12
	s_nop 0
	v_mul_f32_e32 v13, 0x3f317217, v12
	v_fma_f32 v13, v12, s57, -v13
	v_fmac_f32_e32 v13, 0x3377d1cf, v12
	v_fmac_f32_e32 v13, 0x3f317217, v12
	v_cmp_lt_f32_e64 s[0:1], |v12|, s8
	s_nop 1
	v_cndmask_b32_e64 v12, v12, v13, s[0:1]
	v_cndmask_b32_e32 v13, 0, v201, vcc
	v_sub_f32_e32 v12, v12, v13
	v_mul_f32_e32 v13, 0xbfb8aa3b, v45
	v_exp_f32_e32 v13, v13
	s_nop 0
	v_add_f32_e32 v13, 1.0, v13
	v_div_scale_f32 v39, s[0:1], v13, v13, 1.0
	v_rcp_f32_e32 v41, v39
	s_nop 0
	v_fma_f32 v43, -v39, v41, 1.0
	v_fmac_f32_e32 v41, v43, v41
	v_div_scale_f32 v43, vcc, 1.0, v13, 1.0
	v_mul_f32_e32 v45, v43, v41
	v_fma_f32 v64, -v39, v45, v43
	v_fmac_f32_e32 v45, v64, v41
	v_fma_f32 v39, -v39, v45, v43
	v_div_fmas_f32 v39, v39, v41, v45
	v_div_fixup_f32 v13, v39, v13, 1.0
	v_fma_f32 v13, v23, v13, v9
	v_max_f32_e32 v13, 0xda24260, v13
	v_cmp_gt_f32_e32 vcc, s56, v13
	s_nop 1
	v_cndmask_b32_e64 v39, 0, 32, vcc
	v_ldexp_f32 v13, v13, v39
	v_log_f32_e32 v13, v13
	s_nop 0
	v_mul_f32_e32 v39, 0x3f317217, v13
	v_fma_f32 v39, v13, s57, -v39
	v_fmac_f32_e32 v39, 0x3377d1cf, v13
	v_fmac_f32_e32 v39, 0x3f317217, v13
	v_cmp_lt_f32_e64 s[0:1], |v13|, s8
	s_nop 1
	v_cndmask_b32_e64 v13, v13, v39, s[0:1]
	v_cndmask_b32_e32 v39, 0, v201, vcc
	v_sub_f32_e32 v13, v13, v39
	v_mul_f32_e32 v39, 0xbfb8aa3b, v62
	v_exp_f32_e32 v39, v39
	s_nop 0
	v_add_f32_e32 v39, 1.0, v39
	v_div_scale_f32 v41, s[0:1], v39, v39, 1.0
	v_rcp_f32_e32 v43, v41
	s_nop 0
	v_fma_f32 v45, -v41, v43, 1.0
	v_fmac_f32_e32 v43, v45, v43
	v_div_scale_f32 v45, vcc, 1.0, v39, 1.0
	v_mul_f32_e32 v62, v45, v43
	v_fma_f32 v64, -v41, v62, v45
	v_fmac_f32_e32 v62, v64, v43
	v_fma_f32 v41, -v41, v62, v45
	v_div_fmas_f32 v41, v41, v43, v62
	v_div_fixup_f32 v39, v41, v39, 1.0
	v_fma_f32 v39, v22, v39, v2
	v_max_f32_e32 v39, 0xda24260, v39
	v_cmp_gt_f32_e32 vcc, s56, v39
	s_nop 1
	v_cndmask_b32_e64 v41, 0, 32, vcc
	v_ldexp_f32 v39, v39, v41
	v_log_f32_e32 v39, v39
	s_nop 0
	v_mul_f32_e32 v41, 0x3f317217, v39
	v_fma_f32 v41, v39, s57, -v41
	v_fmac_f32_e32 v41, 0x3377d1cf, v39
	v_fmac_f32_e32 v41, 0x3f317217, v39
	v_cmp_lt_f32_e64 s[0:1], |v39|, s8
	s_nop 1
	v_cndmask_b32_e64 v39, v39, v41, s[0:1]
	v_cndmask_b32_e32 v41, 0, v201, vcc
	v_sub_f32_e32 v62, v39, v41
	v_mul_f32_e32 v39, 0xbfb8aa3b, v63
	v_exp_f32_e32 v39, v39
	s_nop 0
	v_add_f32_e32 v39, 1.0, v39
	v_div_scale_f32 v41, s[0:1], v39, v39, 1.0
	v_rcp_f32_e32 v43, v41
	s_nop 0
	v_fma_f32 v45, -v41, v43, 1.0
	v_fmac_f32_e32 v43, v45, v43
	v_div_scale_f32 v45, vcc, 1.0, v39, 1.0
	v_mul_f32_e32 v63, v45, v43
	v_fma_f32 v64, -v41, v63, v45
	v_fmac_f32_e32 v63, v64, v43
	v_fma_f32 v41, -v41, v63, v45
	v_div_fmas_f32 v41, v41, v43, v63
; __device__ __forceinline__ float sigmoidf_(float x) { return 1.0f / (1.0f + __expf(-x)); }
; __device__ __forceinline__ void hg_bcum(const Params& p, int l, const u16* Uhg, int t0, int h, float* bc, float* lbs,
;                                         float* tots) {
;     ...
;   for (int k = 0; k < 4; ++k) {
;     const int s = (tid >> 4) + 16 * k, d0 = (tid & 15) * 8;
;     float z[8];
;     unpack8(*(const uint4*)(Uhg + (size_t)(t0 + s) * 2048 + 512 + h * 128 + d0), z);
;     float lf[8];
; #pragma unroll
;     for (int j = 0; j < 8; ++j) {
;       const float lbv = lbs[d0 + j];
;       const float f = lbv + (1.0f - lbv) * sigmoidf_(z[j]);
;       lf[j] = __logf(fmaxf(f, 1e-30f));
;     }
;     *(float4*)(bc + s * BCS + d0) = make_float4(lf[0], lf[1], lf[2], lf[3]);
;     *(float4*)(bc + s * BCS + d0 + 4) = make_float4(lf[4], lf[5], lf[6], lf[7]);
	v_div_fixup_f32 v39, v41, v39, 1.0
	v_fma_f32 v39, v21, v39, v3
	v_max_f32_e32 v39, 0xda24260, v39
	v_cmp_gt_f32_e32 vcc, s56, v39
	s_nop 1
	v_cndmask_b32_e64 v41, 0, 32, vcc
	v_ldexp_f32 v39, v39, v41
	v_log_f32_e32 v39, v39
	s_nop 0
	v_mul_f32_e32 v41, 0x3f317217, v39
	v_fma_f32 v41, v39, s57, -v41
	v_fmac_f32_e32 v41, 0x3377d1cf, v39
	v_fmac_f32_e32 v41, 0x3f317217, v39
	v_cmp_lt_f32_e64 s[0:1], |v39|, s8
	s_nop 1
	v_cndmask_b32_e64 v39, v39, v41, s[0:1]
	v_cndmask_b32_e32 v41, 0, v201, vcc
	v_sub_f32_e32 v63, v39, v41
	v_div_scale_f32 v39, s[0:1], v37, v37, 1.0
	v_rcp_f32_e32 v41, v39
	s_nop 0
	v_fma_f32 v43, -v39, v41, 1.0
	v_fmac_f32_e32 v41, v43, v41
	v_div_scale_f32 v43, vcc, 1.0, v37, 1.0
	v_mul_f32_e32 v45, v43, v41
	v_fma_f32 v64, -v39, v45, v43
	v_fmac_f32_e32 v45, v64, v41
	v_fma_f32 v39, -v39, v45, v43
	v_div_fmas_f32 v39, v39, v41, v45
	v_div_fixup_f32 v37, v39, v37, 1.0
	v_fma_f32 v37, v20, v37, v4
	v_max_f32_e32 v37, 0xda24260, v37
	v_cmp_gt_f32_e32 vcc, s56, v37
	s_nop 1
	v_cndmask_b32_e64 v39, 0, 32, vcc
	v_ldexp_f32 v37, v37, v39
	v_log_f32_e32 v37, v37
	s_nop 0
	v_mul_f32_e32 v39, 0x3f317217, v37
	v_fma_f32 v39, v37, s57, -v39
	v_fmac_f32_e32 v39, 0x3377d1cf, v37
	v_fmac_f32_e32 v39, 0x3f317217, v37
	v_cmp_lt_f32_e64 s[0:1], |v37|, s8
	s_nop 1
	v_cndmask_b32_e64 v37, v37, v39, s[0:1]
	v_cndmask_b32_e32 v39, 0, v201, vcc
	v_sub_f32_e32 v64, v37, v39
	v_div_scale_f32 v37, s[0:1], v35, v35, 1.0
	v_rcp_f32_e32 v39, v37
	s_nop 0
	v_fma_f32 v41, -v37, v39, 1.0
	v_fmac_f32_e32 v39, v41, v39
	v_div_scale_f32 v41, vcc, 1.0, v35, 1.0
	v_mul_f32_e32 v43, v41, v39
	v_fma_f32 v45, -v37, v43, v41
	v_fmac_f32_e32 v43, v45, v39
	v_fma_f32 v37, -v37, v43, v41
	v_div_fmas_f32 v37, v37, v39, v43
	v_div_fixup_f32 v35, v37, v35, 1.0
	v_fma_f32 v35, v19, v35, v5
	v_max_f32_e32 v35, 0xda24260, v35
	v_cmp_gt_f32_e32 vcc, s56, v35
	s_nop 1
	v_cndmask_b32_e64 v37, 0, 32, vcc
	v_ldexp_f32 v35, v35, v37
	v_log_f32_e32 v35, v35
	s_nop 0
	v_mul_f32_e32 v37, 0x3f317217, v35
	v_fma_f32 v37, v35, s57, -v37
	v_fmac_f32_e32 v37, 0x3377d1cf, v35
	v_fmac_f32_e32 v37, 0x3f317217, v35
	v_cmp_lt_f32_e64 s[0:1], |v35|, s8
	s_nop 1
	v_cndmask_b32_e64 v35, v35, v37, s[0:1]
	v_cndmask_b32_e32 v37, 0, v201, vcc
	v_sub_f32_e32 v65, v35, v37
	ds_write_b128 v15, v[10:13] offset:8448
	ds_write_b128 v15, v[62:65] offset:8464
	v_or_b32_e32 v10, 32, v14
	v_ashrrev_i32_e32 v11, 31, v10
	v_lshlrev_b64 v[10:11], 12, v[10:11]
	v_lshl_add_u64 v[10:11], s[22:23], 0, v[10:11]
	v_lshl_add_u64 v[10:11], v[10:11], 0, s[58:59]
	v_lshl_add_u64 v[10:11], v[10:11], 0, v[16:17]
	global_load_dwordx4 v[10:13], v[10:11], off offset:1024
	s_waitcnt vmcnt(0)
	v_lshlrev_b32_e32 v35, 16, v10
	v_and_b32_e32 v37, 0xffff0000, v10
	v_mul_f32_e32 v10, 0xbfb8aa3b, v35
	v_exp_f32_e32 v10, v10
	v_lshlrev_b32_e32 v39, 16, v11
	v_and_b32_e32 v41, 0xffff0000, v11
	v_lshlrev_b32_e32 v43, 16, v12
	v_add_f32_e32 v10, 1.0, v10
	v_div_scale_f32 v11, s[0:1], v10, v10, 1.0
	v_and_b32_e32 v45, 0xffff0000, v12
	v_rcp_f32_e32 v12, v11
	v_lshlrev_b32_e32 v64, 16, v13
	v_and_b32_e32 v65, 0xffff0000, v13
	v_fma_f32 v13, -v11, v12, 1.0
	v_fmac_f32_e32 v12, v13, v12
	v_div_scale_f32 v13, vcc, 1.0, v10, 1.0
	v_mul_f32_e32 v35, v13, v12
	v_fma_f32 v62, -v11, v35, v13
	v_fmac_f32_e32 v35, v62, v12
	v_fma_f32 v11, -v11, v35, v13
	v_div_fmas_f32 v11, v11, v12, v35
	v_div_fixup_f32 v10, v11, v10, 1.0
	v_fma_f32 v10, v33, v10, v6
	v_max_f32_e32 v10, 0xda24260, v10
	v_cmp_gt_f32_e32 vcc, s56, v10
	s_nop 1
	v_cndmask_b32_e64 v11, 0, 32, vcc
	v_ldexp_f32 v10, v10, v11
	v_log_f32_e32 v10, v10
	s_nop 0
	v_mul_f32_e32 v11, 0x3f317217, v10
	v_fma_f32 v11, v10, s57, -v11
	v_fmac_f32_e32 v11, 0x3377d1cf, v10
	v_fmac_f32_e32 v11, 0x3f317217, v10
	v_cmp_lt_f32_e64 s[0:1], |v10|, s8
	s_nop 1
	v_cndmask_b32_e64 v10, v10, v11, s[0:1]
	v_cndmask_b32_e32 v11, 0, v201, vcc
	v_sub_f32_e32 v10, v10, v11
	v_mul_f32_e32 v11, 0xbfb8aa3b, v37
	v_exp_f32_e32 v11, v11
	s_nop 0
	v_add_f32_e32 v11, 1.0, v11
	v_div_scale_f32 v12, s[0:1], v11, v11, 1.0
	v_rcp_f32_e32 v13, v12
	s_nop 0
	v_fma_f32 v35, -v12, v13, 1.0
	v_fmac_f32_e32 v13, v35, v13
	v_div_scale_f32 v35, vcc, 1.0, v11, 1.0
	v_mul_f32_e32 v37, v35, v13
	v_fma_f32 v62, -v12, v37, v35
	v_fmac_f32_e32 v37, v62, v13
	v_fma_f32 v12, -v12, v37, v35
	v_div_fmas_f32 v12, v12, v13, v37
	v_div_fixup_f32 v11, v12, v11, 1.0
	v_fma_f32 v11, v25, v11, v7
	v_max_f32_e32 v11, 0xda24260, v11
	v_cmp_gt_f32_e32 vcc, s56, v11
	s_nop 1
	v_cndmask_b32_e64 v12, 0, 32, vcc
	v_ldexp_f32 v11, v11, v12
	v_log_f32_e32 v11, v11
	s_nop 0
	v_mul_f32_e32 v12, 0x3f317217, v11
	v_fma_f32 v12, v11, s57, -v12
	v_fmac_f32_e32 v12, 0x3377d1cf, v11
	v_fmac_f32_e32 v12, 0x3f317217, v11
	v_cmp_lt_f32_e64 s[0:1], |v11|, s8
	s_nop 1
	v_cndmask_b32_e64 v11, v11, v12, s[0:1]
	v_cndmask_b32_e32 v12, 0, v201, vcc
	v_sub_f32_e32 v11, v11, v12
	v_mul_f32_e32 v12, 0xbfb8aa3b, v39
	v_exp_f32_e32 v12, v12
	s_nop 0
	v_add_f32_e32 v12, 1.0, v12
	v_div_scale_f32 v13, s[0:1], v12, v12, 1.0
	v_rcp_f32_e32 v35, v13
	s_nop 0
	v_fma_f32 v37, -v13, v35, 1.0
	v_fmac_f32_e32 v35, v37, v35
	v_div_scale_f32 v37, vcc, 1.0, v12, 1.0
	v_mul_f32_e32 v39, v37, v35
	v_fma_f32 v62, -v13, v39, v37
	v_fmac_f32_e32 v39, v62, v35
	v_fma_f32 v13, -v13, v39, v37
	v_div_fmas_f32 v13, v13, v35, v39
	v_div_fixup_f32 v12, v13, v12, 1.0
	v_fma_f32 v12, v24, v12, v8
	v_max_f32_e32 v12, 0xda24260, v12
	v_cmp_gt_f32_e32 vcc, s56, v12
	s_nop 1
	v_cndmask_b32_e64 v13, 0, 32, vcc
	v_ldexp_f32 v12, v12, v13
	v_log_f32_e32 v12, v12
	s_nop 0
	v_mul_f32_e32 v13, 0x3f317217, v12
	v_fma_f32 v13, v12, s57, -v13
	v_fmac_f32_e32 v13, 0x3377d1cf, v12
	v_fmac_f32_e32 v13, 0x3f317217, v12
; __device__ __forceinline__ float sigmoidf_(float x) { return 1.0f / (1.0f + __expf(-x)); }
; __device__ __forceinline__ void hg_bcum(const Params& p, int l, const u16* Uhg, int t0, int h, float* bc, float* lbs,
;                                         float* tots) {
;     ...
;   for (int k = 0; k < 4; ++k) {
;     const int s = (tid >> 4) + 16 * k, d0 = (tid & 15) * 8;
;     float z[8];
;     unpack8(*(const uint4*)(Uhg + (size_t)(t0 + s) * 2048 + 512 + h * 128 + d0), z);
;     float lf[8];
; #pragma unroll
;     for (int j = 0; j < 8; ++j) {
;       const float lbv = lbs[d0 + j];
;       const float f = lbv + (1.0f - lbv) * sigmoidf_(z[j]);
;       lf[j] = __logf(fmaxf(f, 1e-30f));
;     }
;     *(float4*)(bc + s * BCS + d0) = make_float4(lf[0], lf[1], lf[2], lf[3]);
;     *(float4*)(bc + s * BCS + d0 + 4) = make_float4(lf[4], lf[5], lf[6], lf[7]);
	v_cmp_lt_f32_e64 s[0:1], |v12|, s8
	s_nop 1
	v_cndmask_b32_e64 v12, v12, v13, s[0:1]
	v_cndmask_b32_e32 v13, 0, v201, vcc
	v_sub_f32_e32 v12, v12, v13
	v_mul_f32_e32 v13, 0xbfb8aa3b, v41
	v_exp_f32_e32 v13, v13
	s_nop 0
	v_add_f32_e32 v13, 1.0, v13
	v_div_scale_f32 v35, s[0:1], v13, v13, 1.0
	v_rcp_f32_e32 v37, v35
	s_nop 0
	v_fma_f32 v39, -v35, v37, 1.0
	v_fmac_f32_e32 v37, v39, v37
	v_div_scale_f32 v39, vcc, 1.0, v13, 1.0
	v_mul_f32_e32 v41, v39, v37
	v_fma_f32 v62, -v35, v41, v39
	v_fmac_f32_e32 v41, v62, v37
	v_fma_f32 v35, -v35, v41, v39
	v_div_fmas_f32 v35, v35, v37, v41
	v_div_fixup_f32 v13, v35, v13, 1.0
	v_fma_f32 v13, v23, v13, v9
	v_max_f32_e32 v13, 0xda24260, v13
	v_cmp_gt_f32_e32 vcc, s56, v13
	s_nop 1
	v_cndmask_b32_e64 v35, 0, 32, vcc
	v_ldexp_f32 v13, v13, v35
	v_log_f32_e32 v13, v13
	s_nop 0
	v_mul_f32_e32 v35, 0x3f317217, v13
	v_fma_f32 v35, v13, s57, -v35
	v_fmac_f32_e32 v35, 0x3377d1cf, v13
	v_fmac_f32_e32 v35, 0x3f317217, v13
	v_cmp_lt_f32_e64 s[0:1], |v13|, s8
	s_nop 1
	v_cndmask_b32_e64 v13, v13, v35, s[0:1]
	v_cndmask_b32_e32 v35, 0, v201, vcc
	v_sub_f32_e32 v13, v13, v35
	v_mul_f32_e32 v35, 0xbfb8aa3b, v43
	v_exp_f32_e32 v35, v35
	s_nop 0
	v_add_f32_e32 v35, 1.0, v35
	v_div_scale_f32 v37, s[0:1], v35, v35, 1.0
	v_rcp_f32_e32 v39, v37
	s_nop 0
	v_fma_f32 v41, -v37, v39, 1.0
	v_fmac_f32_e32 v39, v41, v39
	v_div_scale_f32 v41, vcc, 1.0, v35, 1.0
	v_mul_f32_e32 v43, v41, v39
	v_fma_f32 v62, -v37, v43, v41
	v_fmac_f32_e32 v43, v62, v39
	v_fma_f32 v37, -v37, v43, v41
	v_div_fmas_f32 v37, v37, v39, v43
	v_div_fixup_f32 v35, v37, v35, 1.0
	v_fma_f32 v35, v22, v35, v2
	v_max_f32_e32 v35, 0xda24260, v35
	v_cmp_gt_f32_e32 vcc, s56, v35
	s_nop 1
	v_cndmask_b32_e64 v37, 0, 32, vcc
	v_ldexp_f32 v35, v35, v37
	v_log_f32_e32 v35, v35
	s_nop 0
	v_mul_f32_e32 v37, 0x3f317217, v35
	v_fma_f32 v37, v35, s57, -v37
	v_fmac_f32_e32 v37, 0x3377d1cf, v35
	v_fmac_f32_e32 v37, 0x3f317217, v35
	v_cmp_lt_f32_e64 s[0:1], |v35|, s8
	s_nop 1
	v_cndmask_b32_e64 v35, v35, v37, s[0:1]
	v_cndmask_b32_e32 v37, 0, v201, vcc
	v_sub_f32_e32 v62, v35, v37
	v_mul_f32_e32 v35, 0xbfb8aa3b, v45
	v_exp_f32_e32 v35, v35
	s_nop 0
	v_add_f32_e32 v35, 1.0, v35
	v_div_scale_f32 v37, s[0:1], v35, v35, 1.0
	v_rcp_f32_e32 v39, v37
	s_nop 0
	v_fma_f32 v41, -v37, v39, 1.0
	v_fmac_f32_e32 v39, v41, v39
	v_div_scale_f32 v41, vcc, 1.0, v35, 1.0
	v_mul_f32_e32 v43, v41, v39
	v_fma_f32 v45, -v37, v43, v41
	v_fmac_f32_e32 v43, v45, v39
	v_fma_f32 v37, -v37, v43, v41
	v_div_fmas_f32 v37, v37, v39, v43
	v_div_fixup_f32 v35, v37, v35, 1.0
	v_fma_f32 v35, v21, v35, v3
	v_max_f32_e32 v35, 0xda24260, v35
	v_cmp_gt_f32_e32 vcc, s56, v35
	s_nop 1
	v_cndmask_b32_e64 v37, 0, 32, vcc
	v_ldexp_f32 v35, v35, v37
	v_log_f32_e32 v35, v35
	s_nop 0
	v_mul_f32_e32 v37, 0x3f317217, v35
	v_fma_f32 v37, v35, s57, -v37
	v_fmac_f32_e32 v37, 0x3377d1cf, v35
	v_fmac_f32_e32 v37, 0x3f317217, v35
	v_cmp_lt_f32_e64 s[0:1], |v35|, s8
	s_nop 1
	v_cndmask_b32_e64 v35, v35, v37, s[0:1]
	v_cndmask_b32_e32 v37, 0, v201, vcc
	v_sub_f32_e32 v63, v35, v37
	v_mul_f32_e32 v35, 0xbfb8aa3b, v64
	v_exp_f32_e32 v35, v35
	s_nop 0
	v_add_f32_e32 v35, 1.0, v35
	v_div_scale_f32 v37, s[0:1], v35, v35, 1.0
	v_rcp_f32_e32 v39, v37
	s_nop 0
	v_fma_f32 v41, -v37, v39, 1.0
	v_fmac_f32_e32 v39, v41, v39
	v_div_scale_f32 v41, vcc, 1.0, v35, 1.0
	v_mul_f32_e32 v43, v41, v39
	v_fma_f32 v45, -v37, v43, v41
	v_fmac_f32_e32 v43, v45, v39
	v_fma_f32 v37, -v37, v43, v41
	v_div_fmas_f32 v37, v37, v39, v43
	v_div_fixup_f32 v35, v37, v35, 1.0
	v_fma_f32 v35, v20, v35, v4
	v_max_f32_e32 v35, 0xda24260, v35
	v_cmp_gt_f32_e32 vcc, s56, v35
	s_nop 1
	v_cndmask_b32_e64 v37, 0, 32, vcc
	v_ldexp_f32 v35, v35, v37
	v_log_f32_e32 v35, v35
	s_nop 0
	v_mul_f32_e32 v37, 0x3f317217, v35
	v_fma_f32 v37, v35, s57, -v37
	v_fmac_f32_e32 v37, 0x3377d1cf, v35
	v_fmac_f32_e32 v37, 0x3f317217, v35
	v_cmp_lt_f32_e64 s[0:1], |v35|, s8
	s_nop 1
	v_cndmask_b32_e64 v35, v35, v37, s[0:1]
	v_cndmask_b32_e32 v37, 0, v201, vcc
	v_sub_f32_e32 v64, v35, v37
	v_mul_f32_e32 v35, 0xbfb8aa3b, v65
	v_exp_f32_e32 v35, v35
	s_nop 0
	v_add_f32_e32 v35, 1.0, v35
	v_div_scale_f32 v37, s[0:1], v35, v35, 1.0
	v_rcp_f32_e32 v39, v37
	s_nop 0
	v_fma_f32 v41, -v37, v39, 1.0
	v_fmac_f32_e32 v39, v41, v39
	v_div_scale_f32 v41, vcc, 1.0, v35, 1.0
	v_mul_f32_e32 v43, v41, v39
	v_fma_f32 v45, -v37, v43, v41
	v_fmac_f32_e32 v43, v45, v39
	v_fma_f32 v37, -v37, v43, v41
	v_div_fmas_f32 v37, v37, v39, v43
	v_div_fixup_f32 v35, v37, v35, 1.0
	v_fma_f32 v35, v19, v35, v5
	v_max_f32_e32 v35, 0xda24260, v35
	v_cmp_gt_f32_e32 vcc, s56, v35
	s_nop 1
	v_cndmask_b32_e64 v37, 0, 32, vcc
	v_ldexp_f32 v35, v35, v37
	v_log_f32_e32 v35, v35
	s_nop 0
	v_mul_f32_e32 v37, 0x3f317217, v35
	v_fma_f32 v37, v35, s57, -v37
	v_fmac_f32_e32 v37, 0x3377d1cf, v35
	v_fmac_f32_e32 v37, 0x3f317217, v35
	v_cmp_lt_f32_e64 s[0:1], |v35|, s8
	s_nop 1
	v_cndmask_b32_e64 v35, v35, v37, s[0:1]
	v_cndmask_b32_e32 v37, 0, v201, vcc
	v_sub_f32_e32 v65, v35, v37
	ds_write_b128 v15, v[10:13] offset:16896
	ds_write_b128 v15, v[62:65] offset:16912
	v_or_b32_e32 v10, 48, v14
	v_ashrrev_i32_e32 v11, 31, v10
	v_lshlrev_b64 v[10:11], 12, v[10:11]
	v_lshl_add_u64 v[10:11], s[22:23], 0, v[10:11]
	v_lshl_add_u64 v[10:11], v[10:11], 0, s[58:59]
	v_lshl_add_u64 v[10:11], v[10:11], 0, v[16:17]
	global_load_dwordx4 v[10:13], v[10:11], off offset:1024
	s_waitcnt vmcnt(0)
; __device__ __forceinline__ float sigmoidf_(float x) { return 1.0f / (1.0f + __expf(-x)); }
; __device__ __forceinline__ void hg_bcum(const Params& p, int l, const u16* Uhg, int t0, int h, float* bc, float* lbs,
;                                         float* tots) {
;     ...
;   for (int k = 0; k < 4; ++k) {
;     const int s = (tid >> 4) + 16 * k, d0 = (tid & 15) * 8;
;     float z[8];
;     unpack8(*(const uint4*)(Uhg + (size_t)(t0 + s) * 2048 + 512 + h * 128 + d0), z);
;     float lf[8];
; #pragma unroll
;     for (int j = 0; j < 8; ++j) {
;       const float lbv = lbs[d0 + j];
;       const float f = lbv + (1.0f - lbv) * sigmoidf_(z[j]);
;       lf[j] = __logf(fmaxf(f, 1e-30f));
;     }
;     *(float4*)(bc + s * BCS + d0) = make_float4(lf[0], lf[1], lf[2], lf[3]);
;     *(float4*)(bc + s * BCS + d0 + 4) = make_float4(lf[4], lf[5], lf[6], lf[7]);
	v_lshlrev_b32_e32 v14, 16, v10
	v_and_b32_e32 v16, 0xffff0000, v10
	v_lshlrev_b32_e32 v17, 16, v11
	v_and_b32_e32 v35, 0xffff0000, v11
	v_lshlrev_b32_e32 v11, 16, v13
	v_and_b32_e32 v10, 0xffff0000, v13
	v_mul_f32_e32 v13, 0xbfb8aa3b, v14
	v_exp_f32_e32 v13, v13
	v_lshlrev_b32_e32 v37, 16, v12
	v_and_b32_e32 v12, 0xffff0000, v12
	v_mul_f32_e32 v12, 0xbfb8aa3b, v12
	v_add_f32_e32 v13, 1.0, v13
	v_div_scale_f32 v14, s[0:1], v13, v13, 1.0
	v_rcp_f32_e32 v39, v14
	v_exp_f32_e32 v12, v12
	v_mul_f32_e32 v11, 0xbfb8aa3b, v11
	v_exp_f32_e32 v11, v11
	v_fma_f32 v41, -v14, v39, 1.0
	v_fmac_f32_e32 v39, v41, v39
	v_div_scale_f32 v41, vcc, 1.0, v13, 1.0
	v_mul_f32_e32 v43, v41, v39
	v_fma_f32 v45, -v14, v43, v41
	v_fmac_f32_e32 v43, v45, v39
	v_fma_f32 v14, -v14, v43, v41
	v_div_fmas_f32 v14, v14, v39, v43
	v_div_fixup_f32 v13, v14, v13, 1.0
	v_fma_f32 v6, v33, v13, v6
	v_max_f32_e32 v6, 0xda24260, v6
	v_cmp_gt_f32_e32 vcc, s56, v6
	v_add_f32_e32 v12, 1.0, v12
	v_add_f32_e32 v11, 1.0, v11
	v_cndmask_b32_e64 v13, 0, 32, vcc
	v_ldexp_f32 v6, v6, v13
	v_log_f32_e32 v6, v6
	v_mul_f32_e32 v10, 0xbfb8aa3b, v10
	v_exp_f32_e32 v10, v10
	v_mul_f32_e32 v13, 0x3f317217, v6
	v_fma_f32 v13, v6, s57, -v13
	v_fmac_f32_e32 v13, 0x3377d1cf, v6
	v_fmac_f32_e32 v13, 0x3f317217, v6
	v_cmp_lt_f32_e64 s[0:1], |v6|, s8
	v_add_f32_e32 v10, 1.0, v10
	s_nop 0
	v_cndmask_b32_e64 v6, v6, v13, s[0:1]
	v_cndmask_b32_e32 v13, 0, v201, vcc
	v_sub_f32_e32 v6, v6, v13
	v_mul_f32_e32 v13, 0xbfb8aa3b, v16
	v_exp_f32_e32 v13, v13
	s_nop 0
	v_add_f32_e32 v13, 1.0, v13
	v_div_scale_f32 v14, s[0:1], v13, v13, 1.0
	v_rcp_f32_e32 v16, v14
	s_nop 0
	v_fma_f32 v33, -v14, v16, 1.0
	v_fmac_f32_e32 v16, v33, v16
	v_div_scale_f32 v33, vcc, 1.0, v13, 1.0
	v_mul_f32_e32 v39, v33, v16
	v_fma_f32 v41, -v14, v39, v33
	v_fmac_f32_e32 v39, v41, v16
	v_fma_f32 v14, -v14, v39, v33
	v_div_fmas_f32 v14, v14, v16, v39
	v_div_fixup_f32 v13, v14, v13, 1.0
	v_fma_f32 v7, v25, v13, v7
	v_max_f32_e32 v7, 0xda24260, v7
	v_cmp_gt_f32_e32 vcc, s56, v7
	s_nop 1
	v_cndmask_b32_e64 v13, 0, 32, vcc
	v_ldexp_f32 v7, v7, v13
	v_log_f32_e32 v7, v7
	s_nop 0
	v_mul_f32_e32 v13, 0x3f317217, v7
	v_fma_f32 v13, v7, s57, -v13
	v_fmac_f32_e32 v13, 0x3377d1cf, v7
	v_fmac_f32_e32 v13, 0x3f317217, v7
	v_cmp_lt_f32_e64 s[0:1], |v7|, s8
	s_nop 1
	v_cndmask_b32_e64 v7, v7, v13, s[0:1]
	v_cndmask_b32_e32 v13, 0, v201, vcc
	v_sub_f32_e32 v7, v7, v13
	v_mul_f32_e32 v13, 0xbfb8aa3b, v17
	v_exp_f32_e32 v13, v13
	s_nop 0
	v_add_f32_e32 v13, 1.0, v13
	v_div_scale_f32 v14, s[0:1], v13, v13, 1.0
	v_rcp_f32_e32 v16, v14
	s_nop 0
	v_fma_f32 v17, -v14, v16, 1.0
	v_fmac_f32_e32 v16, v17, v16
	v_div_scale_f32 v17, vcc, 1.0, v13, 1.0
	v_mul_f32_e32 v25, v17, v16
	v_fma_f32 v33, -v14, v25, v17
	v_fmac_f32_e32 v25, v33, v16
	v_fma_f32 v14, -v14, v25, v17
	v_div_fmas_f32 v14, v14, v16, v25
	v_div_fixup_f32 v13, v14, v13, 1.0
	v_fma_f32 v8, v24, v13, v8
	v_max_f32_e32 v8, 0xda24260, v8
	v_cmp_gt_f32_e32 vcc, s56, v8
	s_nop 1
	v_cndmask_b32_e64 v13, 0, 32, vcc
	v_ldexp_f32 v8, v8, v13
	v_log_f32_e32 v8, v8
	s_nop 0
	v_mul_f32_e32 v13, 0x3f317217, v8
	v_fma_f32 v13, v8, s57, -v13
	v_fmac_f32_e32 v13, 0x3377d1cf, v8
	v_fmac_f32_e32 v13, 0x3f317217, v8
	v_cmp_lt_f32_e64 s[0:1], |v8|, s8
	s_nop 1
	v_cndmask_b32_e64 v8, v8, v13, s[0:1]
	v_cndmask_b32_e32 v13, 0, v201, vcc
	v_sub_f32_e32 v8, v8, v13
	v_mul_f32_e32 v13, 0xbfb8aa3b, v35
	v_exp_f32_e32 v13, v13
	s_nop 0
	v_add_f32_e32 v13, 1.0, v13
	v_div_scale_f32 v14, s[0:1], v13, v13, 1.0
	v_rcp_f32_e32 v16, v14
	s_nop 0
	v_fma_f32 v17, -v14, v16, 1.0
	v_fmac_f32_e32 v16, v17, v16
	v_div_scale_f32 v17, vcc, 1.0, v13, 1.0
	v_mul_f32_e32 v24, v17, v16
	v_fma_f32 v25, -v14, v24, v17
	v_fmac_f32_e32 v24, v25, v16
	v_fma_f32 v14, -v14, v24, v17
	v_div_fmas_f32 v14, v14, v16, v24
	v_div_fixup_f32 v13, v14, v13, 1.0
	v_fmac_f32_e32 v9, v23, v13
	v_max_f32_e32 v9, 0xda24260, v9
	v_cmp_gt_f32_e32 vcc, s56, v9
	s_nop 1
	v_cndmask_b32_e64 v13, 0, 32, vcc
	v_ldexp_f32 v9, v9, v13
	v_log_f32_e32 v9, v9
	s_nop 0
	v_mul_f32_e32 v13, 0x3f317217, v9
	v_fma_f32 v13, v9, s57, -v13
	v_fmac_f32_e32 v13, 0x3377d1cf, v9
	v_fmac_f32_e32 v13, 0x3f317217, v9
	v_cmp_lt_f32_e64 s[0:1], |v9|, s8
	s_nop 1
	v_cndmask_b32_e64 v9, v9, v13, s[0:1]
	v_cndmask_b32_e32 v13, 0, v201, vcc
	v_sub_f32_e32 v9, v9, v13
	v_mul_f32_e32 v13, 0xbfb8aa3b, v37
	v_exp_f32_e32 v13, v13
	s_nop 0
	v_add_f32_e32 v13, 1.0, v13
	v_div_scale_f32 v14, s[0:1], v13, v13, 1.0
	v_rcp_f32_e32 v16, v14
	s_nop 0
	v_fma_f32 v17, -v14, v16, 1.0
	v_fmac_f32_e32 v16, v17, v16
	v_div_scale_f32 v17, vcc, 1.0, v13, 1.0
	v_mul_f32_e32 v23, v17, v16
	v_fma_f32 v24, -v14, v23, v17
	v_fmac_f32_e32 v23, v24, v16
	v_fma_f32 v14, -v14, v23, v17
	v_div_fmas_f32 v14, v14, v16, v23
	v_div_fixup_f32 v13, v14, v13, 1.0
	v_fma_f32 v2, v22, v13, v2
	v_max_f32_e32 v2, 0xda24260, v2
	v_cmp_gt_f32_e32 vcc, s56, v2
	s_nop 1
	v_cndmask_b32_e64 v13, 0, 32, vcc
	v_ldexp_f32 v2, v2, v13
	v_log_f32_e32 v2, v2
	s_nop 0
	v_mul_f32_e32 v13, 0x3f317217, v2
	v_fma_f32 v13, v2, s57, -v13
	v_fmac_f32_e32 v13, 0x3377d1cf, v2
	v_fmac_f32_e32 v13, 0x3f317217, v2
	v_cmp_lt_f32_e64 s[0:1], |v2|, s8
	s_nop 1
	v_cndmask_b32_e64 v2, v2, v13, s[0:1]
	v_cndmask_b32_e32 v13, 0, v201, vcc
	v_sub_f32_e32 v2, v2, v13
	v_div_scale_f32 v13, s[0:1], v12, v12, 1.0
	v_rcp_f32_e32 v14, v13
	s_nop 0
	v_fma_f32 v16, -v13, v14, 1.0
	v_fmac_f32_e32 v14, v16, v14
	v_div_scale_f32 v16, vcc, 1.0, v12, 1.0
	v_mul_f32_e32 v17, v16, v14
	v_fma_f32 v22, -v13, v17, v16
	v_fmac_f32_e32 v17, v22, v14
	v_fma_f32 v13, -v13, v17, v16
	v_div_fmas_f32 v13, v13, v14, v17
	v_div_fixup_f32 v12, v13, v12, 1.0
	v_fma_f32 v3, v21, v12, v3
; __device__ __forceinline__ void hg_bcum(const Params& p, int l, const u16* Uhg, int t0, int h, float* bc, float* lbs,
;                                         float* tots) {
;     ...
;     *(float4*)(bc + s * BCS + d0) = make_float4(lf[0], lf[1], lf[2], lf[3]);
;     *(float4*)(bc + s * BCS + d0 + 4) = make_float4(lf[4], lf[5], lf[6], lf[7]);
;   }
;   __syncthreads();
;   {
;     const int d = tid & 127, hf = tid >> 7;
;     float r[32];
;     float run = 0.f;
; #pragma unroll
;     for (int s = 0; s < 32; ++s) { run += bc[(hf * 32 + s) * BCS + d]; r[s] = run; }
;     if (hf == 0) tots[d] = run;
;     __syncthreads();
	v_max_f32_e32 v3, 0xda24260, v3
	v_cmp_gt_f32_e32 vcc, s56, v3
	s_nop 1
	v_cndmask_b32_e64 v12, 0, 32, vcc
	v_ldexp_f32 v3, v3, v12
	v_log_f32_e32 v3, v3
	s_nop 0
	v_mul_f32_e32 v12, 0x3f317217, v3
	v_fma_f32 v12, v3, s57, -v12
	v_fmac_f32_e32 v12, 0x3377d1cf, v3
	v_fmac_f32_e32 v12, 0x3f317217, v3
	v_cmp_lt_f32_e64 s[0:1], |v3|, s8
	s_nop 1
	v_cndmask_b32_e64 v3, v3, v12, s[0:1]
	v_cndmask_b32_e32 v12, 0, v201, vcc
	v_sub_f32_e32 v3, v3, v12
	v_div_scale_f32 v12, s[0:1], v11, v11, 1.0
	v_rcp_f32_e32 v13, v12
	s_nop 0
	v_fma_f32 v14, -v12, v13, 1.0
	v_fmac_f32_e32 v13, v14, v13
	v_div_scale_f32 v14, vcc, 1.0, v11, 1.0
	v_mul_f32_e32 v16, v14, v13
	v_fma_f32 v17, -v12, v16, v14
	v_fmac_f32_e32 v16, v17, v13
	v_fma_f32 v12, -v12, v16, v14
	v_div_fmas_f32 v12, v12, v13, v16
	v_div_fixup_f32 v11, v12, v11, 1.0
	v_fma_f32 v4, v20, v11, v4
	v_max_f32_e32 v4, 0xda24260, v4
	v_cmp_gt_f32_e32 vcc, s56, v4
	s_nop 1
	v_cndmask_b32_e64 v11, 0, 32, vcc
	v_ldexp_f32 v4, v4, v11
	v_log_f32_e32 v4, v4
	s_nop 0
	v_mul_f32_e32 v11, 0x3f317217, v4
	v_fma_f32 v11, v4, s57, -v11
	v_fmac_f32_e32 v11, 0x3377d1cf, v4
	v_fmac_f32_e32 v11, 0x3f317217, v4
	v_cmp_lt_f32_e64 s[0:1], |v4|, s8
	s_nop 1
	v_cndmask_b32_e64 v4, v4, v11, s[0:1]
	v_cndmask_b32_e32 v11, 0, v201, vcc
	v_sub_f32_e32 v4, v4, v11
	v_div_scale_f32 v11, s[0:1], v10, v10, 1.0
	v_rcp_f32_e32 v12, v11
	s_nop 0
	v_fma_f32 v13, -v11, v12, 1.0
	v_fmac_f32_e32 v12, v13, v12
	v_div_scale_f32 v13, vcc, 1.0, v10, 1.0
	v_mul_f32_e32 v14, v13, v12
	v_fma_f32 v16, -v11, v14, v13
	v_fmac_f32_e32 v14, v16, v12
	v_fma_f32 v11, -v11, v14, v13
	v_div_fmas_f32 v11, v11, v12, v14
	v_div_fixup_f32 v10, v11, v10, 1.0
	v_fmac_f32_e32 v5, v19, v10
	v_max_f32_e32 v5, 0xda24260, v5
	v_cmp_gt_f32_e32 vcc, s56, v5
	s_nop 1
	v_cndmask_b32_e64 v10, 0, 32, vcc
	v_ldexp_f32 v5, v5, v10
	v_log_f32_e32 v5, v5
	s_nop 0
	v_mul_f32_e32 v10, 0x3f317217, v5
	v_fma_f32 v10, v5, s57, -v10
	v_fmac_f32_e32 v10, 0x3377d1cf, v5
	v_fmac_f32_e32 v10, 0x3f317217, v5
	v_cmp_lt_f32_e64 s[0:1], |v5|, s8
	s_nop 1
	v_cndmask_b32_e64 v5, v5, v10, s[0:1]
	v_cndmask_b32_e32 v10, 0, v201, vcc
	v_sub_f32_e32 v5, v5, v10
	ds_write_b128 v15, v[6:9] offset:25344
	ds_write_b128 v15, v[2:5] offset:25360
	v_lshrrev_b32_e32 v2, 2, v18
	v_and_b32_e32 v2, 32, v2
	v_mul_u32_u24_e32 v2, 0x210, v2
	v_lshlrev_b32_e32 v3, 2, v80
	v_add3_u32 v2, s69, v2, v3
	s_waitcnt lgkmcnt(0)
	s_barrier
	ds_read2_b32 v[4:5], v2 offset1:132
	v_add_u32_e32 v3, 0x400, v2
	ds_read2_b32 v[6:7], v3 offset0:8 offset1:140
	v_add_u32_e32 v8, 0x800, v2
	ds_read2_b32 v[10:11], v8 offset0:16 offset1:148
	s_waitcnt lgkmcnt(2)
	v_add_f32_e32 v4, 0, v4
	v_add_f32_e32 v5, v4, v5
	s_waitcnt lgkmcnt(1)
	v_add_f32_e32 v6, v5, v6
	v_add_f32_e32 v7, v6, v7
	s_waitcnt lgkmcnt(0)
	v_add_f32_e32 v9, v7, v10
	v_add_f32_e32 v10, v9, v11
	v_add_u32_e32 v11, 0xc00, v2
	ds_read2_b32 v[14:15], v11 offset0:24 offset1:156
	v_add_u32_e32 v12, 0x1000, v2
	ds_read2_b32 v[16:17], v12 offset0:32 offset1:164
	v_add_u32_e32 v20, 0x1800, v2
	ds_read2_b32 v[22:23], v20 offset0:48 offset1:180
	s_waitcnt lgkmcnt(2)
	v_add_f32_e32 v13, v10, v14
	v_add_f32_e32 v14, v13, v15
	s_waitcnt lgkmcnt(1)
	v_add_f32_e32 v15, v14, v16
	v_add_f32_e32 v16, v15, v17
	v_add_u32_e32 v17, 0x1400, v2
	ds_read2_b32 v[18:19], v17 offset0:40 offset1:172
	v_add_u32_e32 v21, 0x1c00, v2
	ds_read2_b32 v[24:25], v21 offset0:56 offset1:188
	v_add_u32_e32 v33, 0x2000, v2
	ds_read2_b32 v[62:63], v33 offset0:64 offset1:196
	s_waitcnt lgkmcnt(2)
	v_add_f32_e32 v18, v16, v18
	v_add_f32_e32 v19, v18, v19
	v_add_f32_e32 v22, v19, v22
	v_add_f32_e32 v23, v22, v23
	s_waitcnt lgkmcnt(1)
	v_add_f32_e32 v24, v23, v24
	v_add_f32_e32 v25, v24, v25
	s_waitcnt lgkmcnt(0)
	v_add_f32_e32 v35, v25, v62
	v_add_u32_e32 v39, 0x2400, v2
	v_add_f32_e32 v37, v35, v63
	ds_read2_b32 v[62:63], v39 offset0:72 offset1:204
	v_add_u32_e32 v41, 0x2800, v2
	v_add_u32_e32 v64, 0x2c00, v2
	ds_read2_b32 v[66:67], v64 offset0:88 offset1:220
	v_add_u32_e32 v68, 0x3400, v2
	s_waitcnt lgkmcnt(1)
	v_add_f32_e32 v43, v37, v62
	v_add_f32_e32 v45, v43, v63
	ds_read2_b32 v[62:63], v41 offset0:80 offset1:212
	ds_read2_b32 v[72:73], v68 offset0:104 offset1:236
	v_add_u32_e32 v76, 0x3c00, v2
	ds_read2_b32 v[78:79], v76 offset0:120 offset1:252
	v_lshl_add_u32 v80, v80, 2, s71
	s_waitcnt lgkmcnt(2)
	v_add_f32_e32 v62, v45, v62
	v_add_f32_e32 v63, v62, v63
	v_add_f32_e32 v65, v63, v66
	v_add_f32_e32 v66, v65, v67
	v_add_u32_e32 v67, 0x3000, v2
	ds_read2_b32 v[70:71], v67 offset0:96 offset1:228
	s_waitcnt lgkmcnt(0)
	v_add_f32_e32 v69, v66, v70
	v_add_f32_e32 v70, v69, v71
	v_add_f32_e32 v71, v70, v72
	v_add_f32_e32 v72, v71, v73
	v_add_u32_e32 v73, 0x3800, v2
	ds_read2_b32 v[74:75], v73 offset0:112 offset1:244
	s_waitcnt lgkmcnt(0)
	v_add_f32_e32 v74, v72, v74
	v_add_f32_e32 v75, v74, v75
	v_add_f32_e32 v77, v75, v78
	v_add_f32_e32 v78, v77, v79
	s_and_saveexec_b64 s[0:1], s[46:47]
	ds_write_b32 v80, v78
	s_or_b64 exec, exec, s[0:1]
	v_mov_b32_e32 v79, 0
	s_waitcnt lgkmcnt(0)
	s_barrier
; __device__ __forceinline__ void hg_bcum(const Params& p, int l, const u16* Uhg, int t0, int h, float* bc, float* lbs,
;                                         float* tots) {
;     ...
;     const float add = hf ? tots[d] : 0.f;
; #pragma unroll
;     for (int s = 0; s < 32; ++s) bc[(hf * 32 + s) * BCS + d] = r[s] + add;
;   }
;   __syncthreads();
; __device__ __forceinline__ void phase_hg_local(const Params& p, int l, char* smem) {
;     ...
;       const int d = tid & 127;
;       const float bl = bc[63 * BCS + d];
;       for (int idx = tid; idx < 64 * 128; idx += 256) {
;         const int s = idx >> 7;
;         const float bs = bc[s * BCS + d];
;         const float bp = s ? bc[(s - 1) * BCS + d] : 0.f;
;         const float kk = 1.0f - __expf(bs - bp);
;         KT[d * 72 + s] = f2bf(kk * __expf(bl - bs));
;         VTs[d * 72 + s] = Uhg[(size_t)(t0 + s) * 2048 + 1024 + h * 128 + d];
;       }
	s_and_saveexec_b64 s[0:1], s[44:45]
	ds_read_b32 v79, v80
	s_or_b64 exec, exec, s[0:1]
	s_waitcnt lgkmcnt(0)
	v_add_f32_e32 v4, v4, v79
	v_add_f32_e32 v5, v5, v79
	ds_write2_b32 v2, v4, v5 offset1:132
	v_add_f32_e32 v2, v6, v79
	v_add_f32_e32 v4, v7, v79
	ds_write2_b32 v3, v2, v4 offset0:8 offset1:140
	v_add_f32_e32 v2, v9, v79
	v_add_f32_e32 v3, v10, v79
	ds_write2_b32 v8, v2, v3 offset0:16 offset1:148
	v_add_f32_e32 v2, v13, v79
	v_add_f32_e32 v3, v14, v79
	ds_write2_b32 v11, v2, v3 offset0:24 offset1:156
	v_add_f32_e32 v2, v15, v79
	v_add_f32_e32 v3, v16, v79
	ds_write2_b32 v12, v2, v3 offset0:32 offset1:164
	v_add_f32_e32 v2, v18, v79
	v_add_f32_e32 v3, v19, v79
	ds_write2_b32 v17, v2, v3 offset0:40 offset1:172
	v_add_f32_e32 v2, v22, v79
	v_add_f32_e32 v3, v23, v79
	ds_write2_b32 v20, v2, v3 offset0:48 offset1:180
	v_add_f32_e32 v2, v24, v79
	v_add_f32_e32 v3, v25, v79
	ds_write2_b32 v21, v2, v3 offset0:56 offset1:188
	v_add_f32_e32 v2, v35, v79
	v_add_f32_e32 v3, v37, v79
	ds_write2_b32 v33, v2, v3 offset0:64 offset1:196
	v_add_f32_e32 v2, v43, v79
	v_add_f32_e32 v3, v45, v79
	ds_write2_b32 v39, v2, v3 offset0:72 offset1:204
	v_add_f32_e32 v2, v62, v79
	v_add_f32_e32 v3, v63, v79
	ds_write2_b32 v41, v2, v3 offset0:80 offset1:212
	v_add_f32_e32 v2, v65, v79
	v_add_f32_e32 v3, v66, v79
	ds_write2_b32 v64, v2, v3 offset0:88 offset1:220
	v_add_f32_e32 v2, v69, v79
	v_add_f32_e32 v3, v70, v79
	ds_write2_b32 v67, v2, v3 offset0:96 offset1:228
	v_add_f32_e32 v2, v71, v79
	v_add_f32_e32 v3, v72, v79
	ds_write2_b32 v68, v2, v3 offset0:104 offset1:236
	v_add_f32_e32 v2, v74, v79
	v_add_f32_e32 v3, v75, v79
	ds_write2_b32 v73, v2, v3 offset0:112 offset1:244
	v_add_f32_e32 v2, v77, v79
	v_add_f32_e32 v3, v78, v79
	ds_write2_b32 v76, v2, v3 offset0:120 offset1:252
	s_waitcnt lgkmcnt(0)
	s_barrier
	ds_read_b32 v4, v47 offset:33264
	s_min_i32 s1, s20, 0x3ff
	s_lshl_b32 s0, s10, 7
	s_lshl_b32 s10, s1, 4
	s_and_b32 s1, s1, 0x7f
	s_and_b32 s10, s10, 0xffffe000
	s_lshl_b32 s1, s1, 6
	s_lshl_b32 s58, s0, 1
	s_or_b32 s21, s10, s1
	v_lshl_add_u64 v[2:3], v[26:27], 0, s[58:59]
	s_mov_b64 s[0:1], 0
	v_mov_b32_e32 v5, v61
	v_mov_b32_e32 v6, v60
	v_mov_b32_e32 v7, v46
	v_add_u32_e32 v8, s21, v60
	v_ashrrev_i32_e32 v9, 31, v8
	v_lshlrev_b64 v[8:9], 12, v[8:9]
	v_lshl_add_u64 v[8:9], v[2:3], 0, v[8:9]
	s_mov_b32 s98, 0x2000
	s_mov_b32 s99, 0
	global_load_ushort v126, v[8:9], off offset:2048
	v_lshl_add_u64 v[8:9], v[8:9], 0, s[98:99]
	global_load_ushort v127, v[8:9], off offset:2048
	v_lshl_add_u64 v[8:9], v[8:9], 0, s[98:99]
	global_load_ushort v128, v[8:9], off offset:2048
	v_lshl_add_u64 v[8:9], v[8:9], 0, s[98:99]
	global_load_ushort v129, v[8:9], off offset:2048
	v_lshl_add_u64 v[8:9], v[8:9], 0, s[98:99]
	global_load_ushort v130, v[8:9], off offset:2048
	v_lshl_add_u64 v[8:9], v[8:9], 0, s[98:99]
	global_load_ushort v131, v[8:9], off offset:2048
	v_lshl_add_u64 v[8:9], v[8:9], 0, s[98:99]
	global_load_ushort v132, v[8:9], off offset:2048
	v_lshl_add_u64 v[8:9], v[8:9], 0, s[98:99]
	global_load_ushort v133, v[8:9], off offset:2048
	v_lshl_add_u64 v[8:9], v[8:9], 0, s[98:99]
	global_load_ushort v134, v[8:9], off offset:2048
	v_lshl_add_u64 v[8:9], v[8:9], 0, s[98:99]
	global_load_ushort v135, v[8:9], off offset:2048
	v_lshl_add_u64 v[8:9], v[8:9], 0, s[98:99]
	global_load_ushort v136, v[8:9], off offset:2048
	v_lshl_add_u64 v[8:9], v[8:9], 0, s[98:99]
	global_load_ushort v137, v[8:9], off offset:2048
	v_lshl_add_u64 v[8:9], v[8:9], 0, s[98:99]
	global_load_ushort v138, v[8:9], off offset:2048
	v_lshl_add_u64 v[8:9], v[8:9], 0, s[98:99]
	global_load_ushort v139, v[8:9], off offset:2048
	v_lshl_add_u64 v[8:9], v[8:9], 0, s[98:99]
	global_load_ushort v140, v[8:9], off offset:2048
	v_lshl_add_u64 v[8:9], v[8:9], 0, s[98:99]
	global_load_ushort v141, v[8:9], off offset:2048
	v_lshl_add_u64 v[8:9], v[8:9], 0, s[98:99]
	global_load_ushort v142, v[8:9], off offset:2048
	v_lshl_add_u64 v[8:9], v[8:9], 0, s[98:99]
	global_load_ushort v143, v[8:9], off offset:2048
	v_lshl_add_u64 v[8:9], v[8:9], 0, s[98:99]
	global_load_ushort v144, v[8:9], off offset:2048
	v_lshl_add_u64 v[8:9], v[8:9], 0, s[98:99]
	global_load_ushort v145, v[8:9], off offset:2048
	v_lshl_add_u64 v[8:9], v[8:9], 0, s[98:99]
	global_load_ushort v146, v[8:9], off offset:2048
	v_lshl_add_u64 v[8:9], v[8:9], 0, s[98:99]
	global_load_ushort v147, v[8:9], off offset:2048
	v_lshl_add_u64 v[8:9], v[8:9], 0, s[98:99]
	global_load_ushort v148, v[8:9], off offset:2048
	v_lshl_add_u64 v[8:9], v[8:9], 0, s[98:99]
	global_load_ushort v149, v[8:9], off offset:2048
	v_lshl_add_u64 v[8:9], v[8:9], 0, s[98:99]
	global_load_ushort v150, v[8:9], off offset:2048
	v_lshl_add_u64 v[8:9], v[8:9], 0, s[98:99]
	global_load_ushort v151, v[8:9], off offset:2048
	v_lshl_add_u64 v[8:9], v[8:9], 0, s[98:99]
	global_load_ushort v152, v[8:9], off offset:2048
	v_lshl_add_u64 v[8:9], v[8:9], 0, s[98:99]
	global_load_ushort v153, v[8:9], off offset:2048
	v_lshl_add_u64 v[8:9], v[8:9], 0, s[98:99]
	global_load_ushort v154, v[8:9], off offset:2048
	v_lshl_add_u64 v[8:9], v[8:9], 0, s[98:99]
	global_load_ushort v155, v[8:9], off offset:2048
	v_lshl_add_u64 v[8:9], v[8:9], 0, s[98:99]
	global_load_ushort v156, v[8:9], off offset:2048
	v_lshl_add_u64 v[8:9], v[8:9], 0, s[98:99]
	global_load_ushort v157, v[8:9], off offset:2048
	s_branch .LBB0_387
.LBB0_386:
	s_or_b64 exec, exec, s[10:11]
	s_waitcnt lgkmcnt(0)
	v_sub_f32_e32 v9, v8, v10
	v_mul_f32_e32 v9, 0x3fb8aa3b, v9
	v_sub_f32_e32 v8, v4, v8
	v_exp_f32_e32 v9, v9
	v_mul_f32_e32 v8, 0x3fb8aa3b, v8
	v_exp_f32_e32 v8, v8
	s_movk_i32 s10, 0x1eff
	v_sub_f32_e32 v9, 1.0, v9
	v_cmp_lt_u32_e32 vcc, s10, v7
	v_mul_f32_e32 v8, v8, v9
	v_cvt_pk_bf16_f32 v8, v8, s0
	ds_write_b16 v5, v8
	v_add_u32_e32 v6, 2, v6
	s_or_b64 s[0:1], vcc, s[0:1]
	v_add_u32_e32 v8, 0x100, v7
	v_add_u32_e32 v5, 4, v5
	v_mov_b32_e32 v7, v8
	s_andn2_b64 exec, exec, s[0:1]
	s_cbranch_execz .LBB0_389

; __device__ __forceinline__ void phase_hg_local(const Params& p, int l, char* smem) {
;     ...
;         VTs[d * 72 + s] = Uhg[(size_t)(t0 + s) * 2048 + 1024 + h * 128 + d];
;       }
;       if (tid < 128) gdec[(size_t)it * 128 + d] = __expf(bl);
.LBB0_389:
	s_or_b64 exec, exec, s[0:1]
	s_waitcnt vmcnt(0)
	ds_write_b16 v61, v126 offset:18432
	ds_write_b16 v61, v127 offset:18436
	ds_write_b16 v61, v128 offset:18440
	ds_write_b16 v61, v129 offset:18444
	ds_write_b16 v61, v130 offset:18448
	ds_write_b16 v61, v131 offset:18452
	ds_write_b16 v61, v132 offset:18456
	ds_write_b16 v61, v133 offset:18460
	ds_write_b16 v61, v134 offset:18464
	ds_write_b16 v61, v135 offset:18468
	ds_write_b16 v61, v136 offset:18472
	ds_write_b16 v61, v137 offset:18476
	ds_write_b16 v61, v138 offset:18480
	ds_write_b16 v61, v139 offset:18484
	ds_write_b16 v61, v140 offset:18488
	ds_write_b16 v61, v141 offset:18492
	ds_write_b16 v61, v142 offset:18496
	ds_write_b16 v61, v143 offset:18500
	ds_write_b16 v61, v144 offset:18504
	ds_write_b16 v61, v145 offset:18508
	ds_write_b16 v61, v146 offset:18512
	ds_write_b16 v61, v147 offset:18516
	ds_write_b16 v61, v148 offset:18520
	ds_write_b16 v61, v149 offset:18524
	ds_write_b16 v61, v150 offset:18528
	ds_write_b16 v61, v151 offset:18532
	ds_write_b16 v61, v152 offset:18536
	ds_write_b16 v61, v153 offset:18540
	ds_write_b16 v61, v154 offset:18544
	ds_write_b16 v61, v155 offset:18548
	ds_write_b16 v61, v156 offset:18552
	ds_write_b16 v61, v157 offset:18556
	s_ashr_i32 s49, s48, 31
	s_and_saveexec_b64 s[0:1], s[42:43]
	s_cbranch_execz .LBB0_375
	v_mul_f32_e32 v2, 0x3fb8aa3b, v4
	v_exp_f32_e32 v4, v2
	s_lshl_b64 s[10:11], s[48:49], 9
	v_lshl_add_u64 v[2:3], v[28:29], 0, s[10:11]
	global_store_dword v[2:3], v4, off
	s_branch .LBB0_375
